# NA tile loop: cross-half row max via v_permlane32_swap instead of ds_bpermute (no LDS round trip), counted lgkmcnt before PV
# baseline (speedup 1.0000x reference)
.LBB0_533:
	s_add_i32 s20, s31, s83
	s_add_i32 s20, s20, -2
	s_cmp_lt_i32 s0, s34
	s_cselect_b64 s[0:1], -1, 0
	s_cmp_le_u32 s68, s20
	s_cselect_b64 s[10:11], -1, 0
	s_or_b64 s[10:11], s[8:9], s[10:11]
	s_cmp_le_u32 s20, s74
	s_cselect_b64 s[12:13], -1, 0
	s_and_b64 s[10:11], s[10:11], s[12:13]
	s_and_b64 s[12:13], s[0:1], s[10:11]
	s_andn2_b64 vcc, exec, s[12:13]
	s_cbranch_vccz .Lna_win
	s_xor_b64 s[0:1], s[0:1], -1
	s_or_b64 s[10:11], s[0:1], s[10:11]
	s_and_b64 vcc, exec, s[10:11]
	s_cbranch_vccz .Lna_next
	s_and_b32 s10, s51, 0xc000
	s_add_i32 s10, s10, 0
	v_add_u32_e32 v0, s10, v235
	v_add_u32_e32 v2, v0, v241
	ds_read_b128 v[80:83], v2
	ds_read_b128 v[84:87], v2 offset:4096
	v_add_u32_e32 v2, v0, v242
	ds_read_b128 v[88:91], v2
	ds_read_b128 v[92:95], v2 offset:4096
	v_add_u32_e32 v2, v0, v243
	v_add_u32_e32 v0, v0, v244
	ds_read_b128 v[96:99], v2
	ds_read_b128 v[100:103], v2 offset:4096
	ds_read_b128 v[104:107], v0
	ds_read_b128 v[108:111], v0 offset:4096
	v_add_u32_e32 v0, s10, v238
	ds_read_b64_tr_b16 v[192:193], v0 offset:8192
	ds_read_b64_tr_b16 v[194:195], v0 offset:8704
	ds_read_b64_tr_b16 v[10:11], v0 offset:9216
	ds_read_b64_tr_b16 v[12:13], v0 offset:9728
	ds_read_b64_tr_b16 v[6:7], v0 offset:10240
	ds_read_b64_tr_b16 v[8:9], v0 offset:10752
	ds_read_b64_tr_b16 v[2:3], v0 offset:11264
	ds_read_b64_tr_b16 v[4:5], v0 offset:11776
	s_setprio 1
	s_waitcnt lgkmcnt(14)
	v_mfma_f32_32x32x16_bf16 v[144:159], v[80:83], v[188:191], v[64:79]
	v_mfma_f32_32x32x16_bf16 v[128:143], v[84:87], v[188:191], v[64:79]
	s_waitcnt lgkmcnt(13)
	v_mfma_f32_32x32x16_bf16 v[144:159], v[88:91], v[184:187], v[144:159]
	s_waitcnt lgkmcnt(12)
	v_mfma_f32_32x32x16_bf16 v[128:143], v[92:95], v[184:187], v[128:143]
	s_waitcnt lgkmcnt(11)
	v_mfma_f32_32x32x16_bf16 v[144:159], v[96:99], v[180:183], v[144:159]
	s_waitcnt lgkmcnt(10)
	v_mfma_f32_32x32x16_bf16 v[128:143], v[100:103], v[180:183], v[128:143]
	s_waitcnt lgkmcnt(9)
	v_mfma_f32_32x32x16_bf16 v[144:159], v[104:107], v[176:179], v[144:159]
	s_waitcnt lgkmcnt(8)
	v_mfma_f32_32x32x16_bf16 v[128:143], v[108:111], v[176:179], v[128:143]
	s_setprio 0
	v_max3_f32 v14, v144, v145, v146
	v_max3_f32 v15, v147, v148, v149
	v_max3_f32 v80, v150, v151, v152
	v_max3_f32 v81, v153, v154, v155
	v_max3_f32 v82, v156, v157, v158
	v_max3_f32 v83, v128, v129, v130
	v_max3_f32 v84, v131, v132, v133
	v_max3_f32 v85, v134, v135, v136
	s_nop 0
	v_max3_f32 v14, v14, v15, v80
	v_max3_f32 v86, v137, v138, v139
	v_max3_f32 v15, v81, v82, v159
	v_max3_f32 v87, v140, v141, v142
	s_xor_b64 s[10:11], s[46:47], -1
	v_max3_f32 v80, v83, v84, v85
	v_max3_f32 v81, v86, v87, v143
	s_nop 0
	v_max3_f32 v14, v14, v15, v80
	v_max_f32_e32 v14, v14, v81
	v_mov_b32_e32 v15, v14
	s_nop 1
	v_permlane32_swap_b32_e32 v15, v14
	v_max_f32_e32 v14, v14, v15
	v_cmp_lt_f32_e32 vcc, s27, v14
	s_or_b64 s[10:11], vcc, s[10:11]
	v_cndmask_b32_e64 v15, 0, 1, s[10:11]
	v_cmp_ne_u32_e32 vcc, 0, v15
	s_cbranch_vccz .Lna_547
	v_max_f32_e32 v15, v14, v14
	v_max_f32_e32 v15, 0, v15
	v_cndmask_b32_e64 v80, v14, v15, s[46:47]
	v_exp_f32_e64 v15, -v80
	v_add_f32_e32 v212, v212, v80
	v_xor_b32_e32 v64, 0x80000000, v212
	v_pk_add_f32 v[144:145], v[144:145], v[80:81] op_sel_hi:[1,0] neg_lo:[0,1] neg_hi:[0,1]
	v_cndmask_b32_e64 v160, 0, v15, s[46:47]
	v_pk_add_f32 v[128:129], v[128:129], v[80:81] op_sel_hi:[1,0] neg_lo:[0,1] neg_hi:[0,1]
	v_pk_add_f32 v[146:147], v[146:147], v[80:81] op_sel_hi:[1,0] neg_lo:[0,1] neg_hi:[0,1]
	v_pk_add_f32 v[130:131], v[130:131], v[80:81] op_sel_hi:[1,0] neg_lo:[0,1] neg_hi:[0,1]
	v_pk_add_f32 v[148:149], v[148:149], v[80:81] op_sel_hi:[1,0] neg_lo:[0,1] neg_hi:[0,1]
	v_pk_add_f32 v[132:133], v[132:133], v[80:81] op_sel_hi:[1,0] neg_lo:[0,1] neg_hi:[0,1]
	v_pk_add_f32 v[150:151], v[150:151], v[80:81] op_sel_hi:[1,0] neg_lo:[0,1] neg_hi:[0,1]
	v_pk_add_f32 v[134:135], v[134:135], v[80:81] op_sel_hi:[1,0] neg_lo:[0,1] neg_hi:[0,1]
	v_pk_add_f32 v[152:153], v[152:153], v[80:81] op_sel_hi:[1,0] neg_lo:[0,1] neg_hi:[0,1]
	v_pk_add_f32 v[136:137], v[136:137], v[80:81] op_sel_hi:[1,0] neg_lo:[0,1] neg_hi:[0,1]
	v_pk_add_f32 v[154:155], v[154:155], v[80:81] op_sel_hi:[1,0] neg_lo:[0,1] neg_hi:[0,1]
	v_pk_add_f32 v[138:139], v[138:139], v[80:81] op_sel_hi:[1,0] neg_lo:[0,1] neg_hi:[0,1]
	v_pk_add_f32 v[156:157], v[156:157], v[80:81] op_sel_hi:[1,0] neg_lo:[0,1] neg_hi:[0,1]
	v_pk_add_f32 v[140:141], v[140:141], v[80:81] op_sel_hi:[1,0] neg_lo:[0,1] neg_hi:[0,1]
	v_pk_add_f32 v[158:159], v[158:159], v[80:81] op_sel_hi:[1,0] neg_lo:[0,1] neg_hi:[0,1]
	v_pk_add_f32 v[142:143], v[142:143], v[80:81] op_sel_hi:[1,0] neg_lo:[0,1] neg_hi:[0,1]
	v_pk_mul_f32 v[30:31], v[30:31], v[160:161] op_sel_hi:[1,0]
	v_pk_mul_f32 v[28:29], v[28:29], v[160:161] op_sel_hi:[1,0]
	v_pk_mul_f32 v[26:27], v[26:27], v[160:161] op_sel_hi:[1,0]
	v_pk_mul_f32 v[24:25], v[24:25], v[160:161] op_sel_hi:[1,0]
	v_pk_mul_f32 v[22:23], v[22:23], v[160:161] op_sel_hi:[1,0]
	v_pk_mul_f32 v[20:21], v[20:21], v[160:161] op_sel_hi:[1,0]
	v_pk_mul_f32 v[18:19], v[18:19], v[160:161] op_sel_hi:[1,0]
	v_pk_mul_f32 v[16:17], v[16:17], v[160:161] op_sel_hi:[1,0]
	v_pk_mul_f32 v[46:47], v[46:47], v[160:161] op_sel_hi:[1,0]
	v_pk_mul_f32 v[44:45], v[44:45], v[160:161] op_sel_hi:[1,0]
	v_pk_mul_f32 v[42:43], v[42:43], v[160:161] op_sel_hi:[1,0]
	v_pk_mul_f32 v[40:41], v[40:41], v[160:161] op_sel_hi:[1,0]
	v_pk_mul_f32 v[38:39], v[38:39], v[160:161] op_sel_hi:[1,0]
	v_pk_mul_f32 v[36:37], v[36:37], v[160:161] op_sel_hi:[1,0]
	v_pk_mul_f32 v[34:35], v[34:35], v[160:161] op_sel_hi:[1,0]
	v_pk_mul_f32 v[32:33], v[32:33], v[160:161] op_sel_hi:[1,0]
	v_mov_b32_e32 v65, v64
	v_mov_b32_e32 v66, v64
	v_mov_b32_e32 v67, v64
	v_mov_b32_e32 v68, v64
	v_mov_b32_e32 v69, v64
	v_mov_b32_e32 v70, v64
	v_mov_b32_e32 v71, v64
	v_mov_b32_e32 v72, v64
	v_mov_b32_e32 v73, v64
	v_mov_b32_e32 v74, v64
	v_mov_b32_e32 v75, v64
	v_mov_b32_e32 v76, v64
	v_mov_b32_e32 v77, v64
	v_mov_b32_e32 v78, v64
	v_mov_b32_e32 v79, v64
	v_pk_mul_f32 v[62:63], v[62:63], v[160:161] op_sel_hi:[1,0]
	v_pk_mul_f32 v[60:61], v[60:61], v[160:161] op_sel_hi:[1,0]
	v_pk_mul_f32 v[58:59], v[58:59], v[160:161] op_sel_hi:[1,0]
	v_pk_mul_f32 v[56:57], v[56:57], v[160:161] op_sel_hi:[1,0]
	v_pk_mul_f32 v[54:55], v[54:55], v[160:161] op_sel_hi:[1,0]
	v_pk_mul_f32 v[52:53], v[52:53], v[160:161] op_sel_hi:[1,0]
	v_pk_mul_f32 v[50:51], v[50:51], v[160:161] op_sel_hi:[1,0]
	v_pk_mul_f32 v[48:49], v[48:49], v[160:161] op_sel_hi:[1,0]
	s_or_b64 s[46:47], s[46:47], exec
.Lna_547:
	v_exp_f32_e32 v15, v144
	v_exp_f32_e32 v144, v128
	v_exp_f32_e32 v128, v145
	v_exp_f32_e32 v129, v129
	v_exp_f32_e32 v145, v146
	v_exp_f32_e32 v130, v130
	v_exp_f32_e32 v146, v147
	v_exp_f32_e32 v131, v131
	v_exp_f32_e32 v147, v148
	v_exp_f32_e32 v148, v132
	v_exp_f32_e32 v149, v149
	v_exp_f32_e32 v218, v133
	v_exp_f32_e32 v150, v150
	v_exp_f32_e32 v219, v134
	v_exp_f32_e32 v151, v151
	v_exp_f32_e32 v220, v135
	v_exp_f32_e32 v132, v152
	v_exp_f32_e32 v133, v136
	v_exp_f32_e32 v134, v153
	v_exp_f32_e32 v135, v137
	v_exp_f32_e32 v137, v154
	v_exp_f32_e32 v138, v138
	v_exp_f32_e32 v152, v155
	v_exp_f32_e32 v139, v139
	v_exp_f32_e32 v153, v156
	v_exp_f32_e32 v154, v140
	v_exp_f32_e32 v155, v157
	v_exp_f32_e32 v156, v141
	v_exp_f32_e32 v157, v158
	v_exp_f32_e32 v158, v142
	v_exp_f32_e32 v159, v159
	v_exp_f32_e32 v143, v143
	v_cvt_pk_bf16_f32 v128, v15, v128
	v_cvt_pk_bf16_f32 v132, v132, v134
	v_cvt_pk_bf16_f32 v136, v144, v129
	v_cvt_pk_bf16_f32 v140, v133, v135
	v_cvt_pk_bf16_f32 v129, v145, v146
	v_cvt_pk_bf16_f32 v133, v137, v152
	v_cvt_pk_bf16_f32 v137, v130, v131
	v_cvt_pk_bf16_f32 v141, v138, v139
	v_cvt_pk_bf16_f32 v130, v147, v149
	v_cvt_pk_bf16_f32 v134, v153, v155
	v_cvt_pk_bf16_f32 v138, v148, v218
	v_cvt_pk_bf16_f32 v142, v154, v156
	v_cvt_pk_bf16_f32 v131, v150, v151
	v_cvt_pk_bf16_f32 v135, v157, v159
	v_cvt_pk_bf16_f32 v139, v219, v220
	v_cvt_pk_bf16_f32 v143, v158, v143
	ds_read_b64_tr_b16 v[144:145], v0 offset:12288
	ds_read_b64_tr_b16 v[146:147], v0 offset:12800
	ds_read_b64_tr_b16 v[148:149], v0 offset:13312
	ds_read_b64_tr_b16 v[150:151], v0 offset:13824
	ds_read_b64_tr_b16 v[152:153], v0 offset:14336
	ds_read_b64_tr_b16 v[154:155], v0 offset:14848
	ds_read_b64_tr_b16 v[156:157], v0 offset:15360
	ds_read_b64_tr_b16 v[158:159], v0 offset:15872
	s_setprio 1
	s_waitcnt lgkmcnt(8)
	v_mfma_f32_32x32x16_bf16 v[16:31], v[192:195], v[128:131], v[16:31]
	s_mov_b32 s61, s60
	s_mov_b32 s62, s60
	s_mov_b32 s63, s60
	v_mfma_f32_32x32x16_bf16 v[16:31], v[10:13], v[132:135], v[16:31]
	v_mfma_f32_32x32x16_bf16 v[16:31], v[6:9], v[136:139], v[16:31]
	v_mfma_f32_32x32x16_bf16 v[16:31], v[2:5], v[140:143], v[16:31]
	v_mov_b64_e32 v[2:3], s[60:61]
	v_mov_b64_e32 v[4:5], s[62:63]
	s_waitcnt lgkmcnt(6)
	v_mfma_f32_32x32x16_bf16 v[32:47], v[144:147], v[128:131], v[32:47]
	v_mfma_f32_32x32x16_bf16 v[48:63], v[2:5], v[128:131], v[48:63]
	s_waitcnt lgkmcnt(4)
	v_mfma_f32_32x32x16_bf16 v[32:47], v[148:151], v[132:135], v[32:47]
	v_mfma_f32_32x32x16_bf16 v[48:63], v[2:5], v[132:135], v[48:63]
	s_waitcnt lgkmcnt(2)
	v_mfma_f32_32x32x16_bf16 v[32:47], v[152:155], v[136:139], v[32:47]
	v_mfma_f32_32x32x16_bf16 v[48:63], v[2:5], v[136:139], v[48:63]
	s_waitcnt lgkmcnt(0)
	v_mfma_f32_32x32x16_bf16 v[32:47], v[156:159], v[140:143], v[32:47]
	v_mfma_f32_32x32x16_bf16 v[48:63], v[2:5], v[140:143], v[48:63]
	s_setprio 0
	s_branch .Lna_next
.Lna_win:
	s_and_b32 s0, s51, 0xc000
	s_add_i32 s10, s0, 0
	v_cmp_lt_u32_e32 vcc, s20, v239
	v_cmp_gt_u32_e64 s[0:1], s20, v240
	v_add3_u32 v0, v249, s83, 6
	s_or_b64 s[0:1], vcc, s[0:1]
	v_cndmask_b32_e64 v0, v0, 0, s[0:1]
	v_mad_u64_u32 v[2:3], s[0:1], v0, v236, v[210:211]
	ds_read2_b32 v[80:81], v2 offset1:1
	ds_read2_b32 v[82:83], v2 offset0:2 offset1:3
	ds_read2_b32 v[84:85], v2 offset0:8 offset1:9
	ds_read2_b32 v[86:87], v2 offset0:10 offset1:11
	ds_read2_b32 v[88:89], v2 offset0:16 offset1:17
	ds_read2_b32 v[90:91], v2 offset0:18 offset1:19
	ds_read2_b32 v[92:93], v2 offset0:24 offset1:25
	ds_read2_b32 v[94:95], v2 offset0:26 offset1:27
	v_add_u32_e32 v0, s10, v237
	v_add_u32_e32 v2, v0, v245
	v_add_u32_e32 v3, v0, v246
	ds_read_b128 v[100:103], v2
	ds_read_b128 v[104:107], v3
	v_add_u32_e32 v2, v0, v247
	v_add_u32_e32 v0, v0, v248
	ds_read_b128 v[108:111], v2
	ds_read_b128 v[112:115], v0
	s_add_i32 s0, s75, s10
	v_add_u32_e32 v0, s0, v238
	ds_read_b64_tr_b16 v[96:97], v0 offset:8192
	ds_read_b64_tr_b16 v[98:99], v0 offset:8704
	ds_read_b64_tr_b16 v[2:3], v0 offset:9216
	ds_read_b64_tr_b16 v[4:5], v0 offset:9728
	ds_read_b64_tr_b16 v[10:11], v0 offset:12288
	ds_read_b64_tr_b16 v[12:13], v0 offset:12800
	ds_read_b64_tr_b16 v[6:7], v0 offset:13312
	ds_read_b64_tr_b16 v[8:9], v0 offset:13824
	s_setprio 1
	s_waitcnt lgkmcnt(11)
	v_mfma_f32_32x32x16_bf16 v[80:95], v[100:103], v[188:191], v[80:95]
	s_waitcnt lgkmcnt(10)
	v_mfma_f32_32x32x16_bf16 v[80:95], v[104:107], v[184:187], v[80:95]
	s_waitcnt lgkmcnt(9)
	v_mfma_f32_32x32x16_bf16 v[80:95], v[108:111], v[180:183], v[80:95]
	s_waitcnt lgkmcnt(8)
	v_mfma_f32_32x32x16_bf16 v[80:95], v[112:115], v[176:179], v[80:95]
	s_setprio 0
	s_nop 10
	v_pk_add_f32 v[14:15], v[80:81], v[212:213] op_sel_hi:[1,0] neg_lo:[0,1] neg_hi:[0,1]
	v_pk_add_f32 v[80:81], v[82:83], v[212:213] op_sel_hi:[1,0] neg_lo:[0,1] neg_hi:[0,1]
	v_pk_add_f32 v[82:83], v[84:85], v[212:213] op_sel_hi:[1,0] neg_lo:[0,1] neg_hi:[0,1]
	v_pk_add_f32 v[84:85], v[86:87], v[212:213] op_sel_hi:[1,0] neg_lo:[0,1] neg_hi:[0,1]
	v_pk_add_f32 v[86:87], v[88:89], v[212:213] op_sel_hi:[1,0] neg_lo:[0,1] neg_hi:[0,1]
	v_pk_add_f32 v[88:89], v[90:91], v[212:213] op_sel_hi:[1,0] neg_lo:[0,1] neg_hi:[0,1]
	v_pk_add_f32 v[90:91], v[92:93], v[212:213] op_sel_hi:[1,0] neg_lo:[0,1] neg_hi:[0,1]
	v_pk_add_f32 v[92:93], v[94:95], v[212:213] op_sel_hi:[1,0] neg_lo:[0,1] neg_hi:[0,1]
	v_max3_f32 v0, v14, v15, v80
	v_max3_f32 v94, v81, v82, v83
	v_max3_f32 v95, v84, v85, v86
	v_max3_f32 v100, v87, v88, v89
	s_mov_b32 s0, 0xefa18f08
	v_max3_f32 v101, v90, v91, v92
	v_max3_f32 v0, v0, v94, v95
	v_max3_f32 v94, v100, v101, v93
	v_max3_f32 v0, v0, v94, v216
	s_xor_b64 s[10:11], s[46:47], -1
	v_mov_b32_e32 v94, v0
	s_nop 1
	v_permlane32_swap_b32_e32 v94, v0
	v_max_f32_e32 v0, v0, v94
	v_cmp_lt_f32_e64 s[0:1], s0, v0
	v_cmp_lt_f32_e32 vcc, s27, v0
	s_and_b64 s[10:11], s[0:1], s[10:11]
	s_or_b64 s[10:11], vcc, s[10:11]
	v_cndmask_b32_e64 v94, 0, 1, s[10:11]
	v_cmp_ne_u32_e32 vcc, 0, v94
	s_cbranch_vccz .Lna_541
	v_max_f32_e32 v64, v0, v0
	v_max_f32_e32 v64, 0, v64
	v_cndmask_b32_e64 v0, 0, v0, s[0:1]
	v_cndmask_b32_e64 v65, v0, v64, s[46:47]
	v_exp_f32_e64 v0, -v65
	v_add_f32_e32 v212, v212, v65
	s_or_b64 s[0:1], s[46:47], s[0:1]
	v_xor_b32_e32 v64, 0x80000000, v212
	v_cndmask_b32_e64 v0, 0, v0, s[46:47]
	s_andn2_b64 s[10:11], s[46:47], exec
	s_and_b64 s[0:1], s[0:1], exec
	v_sub_f32_e32 v14, v14, v65
	v_sub_f32_e32 v15, v15, v65
	v_sub_f32_e32 v80, v80, v65
	v_sub_f32_e32 v81, v81, v65
	v_sub_f32_e32 v82, v82, v65
	v_sub_f32_e32 v83, v83, v65
	v_sub_f32_e32 v84, v84, v65
	v_sub_f32_e32 v85, v85, v65
	v_sub_f32_e32 v86, v86, v65
	v_sub_f32_e32 v87, v87, v65
	v_sub_f32_e32 v88, v88, v65
	v_sub_f32_e32 v89, v89, v65
	v_sub_f32_e32 v90, v90, v65
	v_sub_f32_e32 v91, v91, v65
	v_sub_f32_e32 v92, v92, v65
	v_sub_f32_e32 v93, v93, v65
	v_pk_mul_f32 v[62:63], v[62:63], v[0:1] op_sel_hi:[1,0]
	v_pk_mul_f32 v[60:61], v[60:61], v[0:1] op_sel_hi:[1,0]
	v_pk_mul_f32 v[58:59], v[58:59], v[0:1] op_sel_hi:[1,0]
	v_pk_mul_f32 v[56:57], v[56:57], v[0:1] op_sel_hi:[1,0]
	v_pk_mul_f32 v[54:55], v[54:55], v[0:1] op_sel_hi:[1,0]
	v_pk_mul_f32 v[52:53], v[52:53], v[0:1] op_sel_hi:[1,0]
	v_pk_mul_f32 v[50:51], v[50:51], v[0:1] op_sel_hi:[1,0]
	v_pk_mul_f32 v[48:49], v[48:49], v[0:1] op_sel_hi:[1,0]
	v_pk_mul_f32 v[30:31], v[30:31], v[0:1] op_sel_hi:[1,0]
	v_pk_mul_f32 v[28:29], v[28:29], v[0:1] op_sel_hi:[1,0]
	v_pk_mul_f32 v[26:27], v[26:27], v[0:1] op_sel_hi:[1,0]
	v_pk_mul_f32 v[24:25], v[24:25], v[0:1] op_sel_hi:[1,0]
	v_pk_mul_f32 v[22:23], v[22:23], v[0:1] op_sel_hi:[1,0]
	v_pk_mul_f32 v[20:21], v[20:21], v[0:1] op_sel_hi:[1,0]
	v_pk_mul_f32 v[18:19], v[18:19], v[0:1] op_sel_hi:[1,0]
	v_pk_mul_f32 v[16:17], v[16:17], v[0:1] op_sel_hi:[1,0]
	v_pk_mul_f32 v[46:47], v[46:47], v[0:1] op_sel_hi:[1,0]
	v_pk_mul_f32 v[44:45], v[44:45], v[0:1] op_sel_hi:[1,0]
	v_pk_mul_f32 v[42:43], v[42:43], v[0:1] op_sel_hi:[1,0]
	v_pk_mul_f32 v[40:41], v[40:41], v[0:1] op_sel_hi:[1,0]
	v_pk_mul_f32 v[38:39], v[38:39], v[0:1] op_sel_hi:[1,0]
	v_pk_mul_f32 v[36:37], v[36:37], v[0:1] op_sel_hi:[1,0]
	v_pk_mul_f32 v[34:35], v[34:35], v[0:1] op_sel_hi:[1,0]
	v_pk_mul_f32 v[32:33], v[32:33], v[0:1] op_sel_hi:[1,0]
	v_mov_b32_e32 v65, v64
	v_mov_b32_e32 v66, v64
	v_mov_b32_e32 v67, v64
	v_mov_b32_e32 v68, v64
	v_mov_b32_e32 v69, v64
	v_mov_b32_e32 v70, v64
	v_mov_b32_e32 v71, v64
	v_mov_b32_e32 v72, v64
	v_mov_b32_e32 v73, v64
	v_mov_b32_e32 v74, v64
	v_mov_b32_e32 v75, v64
	v_mov_b32_e32 v76, v64
	v_mov_b32_e32 v77, v64
	v_mov_b32_e32 v78, v64
	v_mov_b32_e32 v79, v64
	s_or_b64 s[46:47], s[10:11], s[0:1]
.Lna_541:
	v_exp_f32_e32 v0, v14
	v_exp_f32_e32 v14, v15
	v_exp_f32_e32 v15, v80
	v_exp_f32_e32 v81, v81
	v_exp_f32_e32 v82, v82
	v_exp_f32_e32 v83, v83
	v_exp_f32_e32 v94, v84
	v_exp_f32_e32 v95, v85
	v_exp_f32_e32 v84, v86
	v_exp_f32_e32 v85, v87
	v_exp_f32_e32 v86, v88
	v_exp_f32_e32 v87, v89
	v_exp_f32_e32 v88, v90
	v_exp_f32_e32 v89, v91
	v_exp_f32_e32 v90, v92
	v_exp_f32_e32 v91, v93
	v_cvt_pk_bf16_f32 v80, v0, v14
	v_cvt_pk_bf16_f32 v84, v84, v85
	v_cvt_pk_bf16_f32 v81, v15, v81
	v_cvt_pk_bf16_f32 v85, v86, v87
	v_cvt_pk_bf16_f32 v82, v82, v83
	v_cvt_pk_bf16_f32 v86, v88, v89
	v_cvt_pk_bf16_f32 v83, v94, v95
	v_cvt_pk_bf16_f32 v87, v90, v91
	s_setprio 1
	s_waitcnt lgkmcnt(0)
	v_mfma_f32_32x32x16_bf16 v[32:47], v[10:13], v[80:83], v[32:47]
	s_mov_b32 s61, s60
	s_mov_b32 s62, s60
	s_mov_b32 s63, s60
	v_mfma_f32_32x32x16_bf16 v[32:47], v[6:9], v[84:87], v[32:47]
	v_mov_b64_e32 v[6:7], s[60:61]
	v_mov_b64_e32 v[8:9], s[62:63]
	v_mfma_f32_32x32x16_bf16 v[16:31], v[96:99], v[80:83], v[16:31]
	s_nop 3
	v_mfma_f32_32x32x16_bf16 v[48:63], v[6:9], v[80:83], v[48:63]
	v_mfma_f32_32x32x16_bf16 v[48:63], v[6:9], v[84:87], v[48:63]
	v_mfma_f32_32x32x16_bf16 v[16:31], v[2:5], v[84:87], v[16:31]
	s_setprio 0
